# grid-size guards on block/wave rotations (same schedule on 256 CUs)
# speedup vs baseline: 1.0074x; 1.0071x over previous
.LBB0_956:
	v_readlane_b32 s0, v254, 19
	s_cmp_lg_u32 s0, 0x100
	s_cbranch_scc1 .Lvmt_norot
	s_add_i32 s77, s77, 192
	s_and_b32 s77, s77, 255
	s_cmp_gt_u32 s77, 63
	s_cselect_b64 s[38:39], -1, 0

.LBB0_1208:
	s_or_b64 exec, exec, s[24:25]
	s_xor_b64 s[24:25], s[2:3], -1
	s_mov_b64 s[20:21], 0
	s_lshl_b64 s[50:51], s[34:35], 20
	s_cmp_eq_u32 s22, 0x800
	s_cselect_b32 s100, 0x300, 0
	v_add_u32_e32 v170, s100, v28
	v_cmp_le_i32_e32 vcc, s22, v170
	v_subrev_u32_e32 v174, s22, v170
	s_nop 0
	v_cndmask_b32_e32 v170, v170, v174, vcc
	v_cmp_gt_i32_e32 vcc, 0x200, v170
	s_and_saveexec_b64 s[2:3], vcc
	s_cbranch_execz .LBB0_1243
	s_add_u32 s23, s92, s20
	s_addc_u32 s26, s93, s21
	s_lshl_b64 s[20:21], s[50:51], 2
	s_add_u32 s20, s23, s20
	s_addc_u32 s21, s26, s21
	v_lshl_add_u64 v[6:7], s[0:1], 0, v[168:169]
	s_mov_b64 s[26:27], 0x500000
	v_lshl_add_u64 v[6:7], v[6:7], 0, s[26:27]
	v_lshlrev_b32_e32 v12, 5, v170
	s_lshl_b32 s23, s22, 5
	s_mov_b64 s[26:27], 0
	v_mov_b32_e32 v13, v170
	s_branch .LBB0_1211

.LBB0_1243:
	s_or_b64 exec, exec, s[2:3]
	s_mov_b64 s[20:21], 0
	s_mov_b64 s[46:47], 0
	s_lshl_b32 s26, s34, 10
	s_mov_b32 s27, s35
	s_cmp_eq_u32 s22, 0x800
	s_cselect_b32 s100, 0x100, 0
	v_add_u32_e32 v170, s100, v28
	v_cmp_le_i32_e32 vcc, s22, v170
	v_subrev_u32_e32 v174, s22, v170
	s_nop 0
	v_cndmask_b32_e32 v170, v170, v174, vcc
	v_cmp_gt_i32_e32 vcc, 0x200, v170
	s_and_saveexec_b64 s[2:3], vcc
	s_cbranch_execz .LBB0_1374
	v_readlane_b32 s52, v252, 16
	v_readlane_b32 s54, v252, 18
	v_readlane_b32 s55, v252, 19
	s_add_u32 s23, s54, s20
	s_addc_u32 s48, s55, s21
	s_lshl_b64 s[20:21], s[50:51], 2
	s_add_u32 s20, s23, s20
	s_addc_u32 s21, s48, s21
	s_add_u32 s23, s94, s46
	s_addc_u32 s48, s95, s47
	s_lshl_b64 s[46:47], s[26:27], 2
	v_readlane_b32 s53, v252, 17
	s_add_u32 s52, s23, s46
	s_addc_u32 s53, s48, s47
	v_lshl_add_u64 v[6:7], s[0:1], 0, v[168:169]
	s_mov_b64 s[46:47], 0x700000
	v_lshl_add_u64 v[6:7], v[6:7], 0, s[46:47]
	v_lshlrev_b32_e32 v79, 5, v170
	s_lshl_b32 s23, s22, 5
	s_mov_b64 s[54:55], 0
	v_mov_b32_e32 v80, v170
	v_readlane_b32 s56, v252, 20
	v_readlane_b32 s57, v252, 21
	v_readlane_b32 s58, v252, 22
	v_readlane_b32 s59, v252, 23
	v_readlane_b32 s60, v252, 24
	v_readlane_b32 s61, v252, 25
	v_readlane_b32 s62, v252, 26
	v_readlane_b32 s63, v252, 27
	v_readlane_b32 s64, v252, 28
	v_readlane_b32 s65, v252, 29
	v_readlane_b32 s66, v252, 30
	v_readlane_b32 s67, v252, 31
	s_branch .LBB0_1247

.LBB0_1374:
	s_or_b64 exec, exec, s[2:3]
	s_mov_b64 s[20:21], 0
	s_cmp_eq_u32 s22, 0x800
	s_cselect_b32 s100, 0x700, 0
	v_add_u32_e32 v170, s100, v28
	v_cmp_le_i32_e32 vcc, s22, v170
	v_subrev_u32_e32 v174, s22, v170
	s_nop 0
	v_cndmask_b32_e32 v170, v170, v174, vcc
	v_cmp_gt_i32_e32 vcc, 0x200, v170
	s_and_saveexec_b64 s[2:3], vcc
	s_cbranch_execz .LBB0_1409
	v_readlane_b32 s52, v252, 16
	v_readlane_b32 s56, v252, 20
	v_readlane_b32 s57, v252, 21
	s_add_u32 s23, s56, s20
	s_addc_u32 s46, s57, s21
	s_lshl_b64 s[20:21], s[50:51], 2
	s_add_u32 s20, s23, s20
	s_addc_u32 s21, s46, s21
	v_lshl_add_u64 v[6:7], s[0:1], 0, v[168:169]
	s_mov_b64 s[46:47], 0x900000
	v_lshl_add_u64 v[6:7], v[6:7], 0, s[46:47]
	v_lshlrev_b32_e32 v12, 5, v170
	s_lshl_b32 s23, s22, 5
	s_mov_b64 s[46:47], 0
	v_mov_b32_e32 v13, v170
	v_readlane_b32 s53, v252, 17
	v_readlane_b32 s54, v252, 18
	v_readlane_b32 s55, v252, 19
	v_readlane_b32 s58, v252, 22
	v_readlane_b32 s59, v252, 23
	v_readlane_b32 s60, v252, 24
	v_readlane_b32 s61, v252, 25
	v_readlane_b32 s62, v252, 26
	v_readlane_b32 s63, v252, 27
	v_readlane_b32 s64, v252, 28
	v_readlane_b32 s65, v252, 29
	v_readlane_b32 s66, v252, 30
	v_readlane_b32 s67, v252, 31
	s_branch .LBB0_1377

.LBB0_1409:
	s_or_b64 exec, exec, s[2:3]
	s_mov_b64 s[20:21], 0
	s_cmp_eq_u32 s22, 0x800
	s_cselect_b32 s100, 0x500, 0
	v_add_u32_e32 v170, s100, v28
	v_cmp_le_i32_e32 vcc, s22, v170
	v_subrev_u32_e32 v174, s22, v170
	s_nop 0
	v_cndmask_b32_e32 v170, v170, v174, vcc
	v_cmp_gt_i32_e32 vcc, 0x200, v170
	s_and_saveexec_b64 s[2:3], vcc
	s_cbranch_execz .LBB0_1444
	v_readlane_b32 s52, v252, 16
	v_readlane_b32 s58, v252, 22
	v_readlane_b32 s59, v252, 23
	s_add_u32 s23, s58, s20
	s_addc_u32 s46, s59, s21
	s_lshl_b64 s[20:21], s[50:51], 2
	s_add_u32 s20, s23, s20
	s_addc_u32 s21, s46, s21
	v_lshl_add_u64 v[6:7], s[0:1], 0, v[168:169]
	s_mov_b64 s[46:47], 0xb00000
	v_lshl_add_u64 v[6:7], v[6:7], 0, s[46:47]
	v_lshlrev_b32_e32 v12, 5, v170
	s_lshl_b32 s23, s22, 5
	s_mov_b64 s[46:47], 0
	v_mov_b32_e32 v13, v170
	v_readlane_b32 s53, v252, 17
	v_readlane_b32 s54, v252, 18
	v_readlane_b32 s55, v252, 19
	v_readlane_b32 s56, v252, 20
	v_readlane_b32 s57, v252, 21
	v_readlane_b32 s60, v252, 24
	v_readlane_b32 s61, v252, 25
	v_readlane_b32 s62, v252, 26
	v_readlane_b32 s63, v252, 27
	v_readlane_b32 s64, v252, 28
	v_readlane_b32 s65, v252, 29
	v_readlane_b32 s66, v252, 30
	v_readlane_b32 s67, v252, 31
	s_branch .LBB0_1412

.LBB0_1444:
	s_or_b64 exec, exec, s[2:3]
	s_mov_b64 s[20:21], 0
	s_cmp_eq_u32 s22, 0x800
	s_cselect_b32 s100, 0x300, 0
	v_add_u32_e32 v170, s100, v28
	v_cmp_le_i32_e32 vcc, s22, v170
	v_subrev_u32_e32 v174, s22, v170
	s_nop 0
	v_cndmask_b32_e32 v170, v170, v174, vcc
	v_cmp_gt_i32_e32 vcc, 0x200, v170
	s_and_saveexec_b64 s[2:3], vcc
	s_cbranch_execz .LBB0_1479
	v_readlane_b32 s52, v252, 16
	v_readlane_b32 s60, v252, 24
	v_readlane_b32 s61, v252, 25
	s_add_u32 s23, s60, s20
	s_addc_u32 s46, s61, s21
	s_lshl_b64 s[20:21], s[50:51], 2
	s_add_u32 s20, s23, s20
	s_addc_u32 s21, s46, s21
	v_lshl_add_u64 v[6:7], s[0:1], 0, v[168:169]
	s_mov_b64 s[46:47], 0xd00000
	v_lshl_add_u64 v[6:7], v[6:7], 0, s[46:47]
	v_lshlrev_b32_e32 v12, 5, v170
	s_lshl_b32 s23, s22, 5
	s_mov_b64 s[46:47], 0
	v_mov_b32_e32 v13, v170
	v_readlane_b32 s53, v252, 17
	v_readlane_b32 s54, v252, 18
	v_readlane_b32 s55, v252, 19
	v_readlane_b32 s56, v252, 20
	v_readlane_b32 s57, v252, 21
	v_readlane_b32 s58, v252, 22
	v_readlane_b32 s59, v252, 23
	v_readlane_b32 s62, v252, 26
	v_readlane_b32 s63, v252, 27
	v_readlane_b32 s64, v252, 28
	v_readlane_b32 s65, v252, 29
	v_readlane_b32 s66, v252, 30
	v_readlane_b32 s67, v252, 31
	s_branch .LBB0_1447

.LBB0_1645:
	s_or_b64 exec, exec, s[20:21]
	s_mov_b64 s[20:21], 0
	s_cmp_eq_u32 s22, 0x800
	s_cselect_b32 s100, 0x100, 0
	v_add_u32_e32 v170, s100, v28
	v_cmp_le_i32_e32 vcc, s22, v170
	v_subrev_u32_e32 v174, s22, v170
	s_nop 0
	v_cndmask_b32_e32 v170, v170, v174, vcc
	v_cmp_gt_i32_e32 vcc, 0x20, v170
	s_and_saveexec_b64 s[2:3], vcc
	s_cbranch_execz .LBB0_1074
	s_add_u32 s23, s88, s20
	s_addc_u32 s26, s89, s21
	s_lshl_b64 s[20:21], s[34:35], 18
	s_add_u32 s20, s23, s20
	v_lshl_add_u64 v[6:7], s[0:1], 0, v[168:169]
	s_mov_b64 s[0:1], 0x1f00000
	s_addc_u32 s21, s26, s21
	v_lshl_add_u64 v[6:7], v[6:7], 0, s[0:1]
	s_lshl_b32 s23, s22, 5
	s_mov_b64 s[0:1], 0
	v_mov_b32_e32 v12, v170
	v_lshlrev_b32_e32 v78, 5, v170
	s_branch .LBB0_1648
